# v112 + raised wave priority for RWKV recurrence blocks (over co-resident weight-prep blocks) in phase 18
# baseline (speedup 1.0000x reference)
; __device__ __forceinline__ int otid() { int t = threadIdx.x; asm volatile("" : "+v"(t)); return t; }
; __device__ __forceinline__ void rwkv_item(const Params& p, int item, float* sm) {
;   const int bh = item >> 2, rg = item & 3;
;   const int b = bh >> 4, h = bh & 15;
;   const bf16_t* rkv = (const bf16_t*)(p.ws + OFF_RKV);
;   const bf16_t* aa = (const bf16_t*)p.out;
;   const bf16_t* wexp = (const bf16_t*)(p.ws + OFF_O);
;   float* SB = (float*)(p.ws + OFF_ZG);
;   float* MU = (float*)(p.ws + OFF_MU);
;   bf16_t* yr = yraw_ptr(p, b);
;   constexpr int TC = 16;
;   constexpr int BUF = 5 * TC * 64 + TC * 16 + TC + TC * 16;
;   const int tid = otid(), lane = tid & 63, wave = tid >> 6;
;   const int sub = lane & 15, rowl = wave * 4 + (lane >> 4);
;   const int ltt = tid >> 4, lrr = tid & 15;
;   const int ch = h * 64 + lane;
;   const float kkw = p.k_k[ch], kaw = p.k_a[ch], rkw = p.r_k[ch];
;   const size_t rowb = (size_t)b * LP;
.LBB0_505:
	s_setprio 3
	s_lshr_b32 s2, s13, 2
	s_and_b32 s18, s13, 3
	s_lshr_b32 s19, s2, 4
	s_and_b32 s2, s2, 15
	s_mul_i32 s22, s19, 0x2080
	s_add_i32 s22, s22, 0x70
	v_readlane_b32 s24, v247, 1
	v_readlane_b32 s25, v247, 2
	v_readlane_b32 s26, v247, 3
	v_readlane_b32 s27, v247, 4
	v_and_b32_e32 v137, 15, v2
	v_lshrrev_b32_e32 v138, 4, v2
	s_add_u32 s4, s26, 0xb600000
	s_addc_u32 s5, s27, 0
	s_mov_b32 s6, s24
	s_mov_b32 s7, s25
	s_add_u32 s8, s26, 0x19d90000
	s_addc_u32 s9, s27, 0
	s_add_u32 s14, s26, 0x18d50000
	s_addc_u32 s15, s27, 0
	s_add_u32 s16, s26, 0x19980000
	s_addc_u32 s17, s27, 0
	s_cmp_lt_u32 s19, 2
	s_cbranch_scc1 .Lrw_ylo
	s_add_i32 s23, s19, -2
	s_mul_i32 s23, s23, 0x1040000
	s_add_u32 s10, s24, 0x4100000
	s_addc_u32 s11, s25, 0
	s_branch .Lrw_yjoin

; __device__ __forceinline__ void rwkv_item(const Params& p, int item, float* sm) {
;     ...
;         const float4 w4 = *(const float4*)(bw + 0 * TC * 64 + t * 64 + sub * 4);
;         const float4 k4 = *(const float4*)(bw + 1 * TC * 64 + t * 64 + sub * 4);
;         const float4 a4 = *(const float4*)(bw + 2 * TC * 64 + t * 64 + sub * 4);
;         const float4 b4 = *(const float4*)(bw + 3 * TC * 64 + t * 64 + sub * 4);
;         const float4 r4 = *(const float4*)(bw + 4 * TC * 64 + t * 64 + sub * 4);
;     ...
;     __syncthreads();
;     {
;       const float* bb = sm + bi * BUF;
;       const float yv = bb[5 * TC * 64 + TC * 16 + TC + ltt * 16 + lrr];
;       const float mu = dpp_sum16(yv) * (1.f / 16.f);
;       yr[(size_t)(t0 + ltt) * D + h * 64 + rg * 16 + lrr] = f2bf(yv - mu);
;       if (lrr == 0) MU[(rowb + t0 + ltt) * 64 + h * 4 + rg] = mu;
;     }
.Lrw_noprep:
	v_add_u32_e32 v46, s1, v135
	v_add_u32_e32 v10, s29, v47
	v_add_u32_e32 v11, s29, v136
	s_waitcnt lgkmcnt(0)
	s_barrier
	ds_read_b32 v120, v46
	ds_read_b128 v[56:59], v10 offset:8192
	ds_read_b128 v[48:51], v10
	ds_read_b128 v[52:55], v10 offset:4096
	ds_read_b128 v[60:63], v10 offset:12288
	ds_read_b128 v[80:83], v10 offset:16384
	ds_read_b128 v[88:91], v11 offset:0
	ds_read_b128 v[92:95], v11 offset:16
	ds_read_b128 v[96:99], v11 offset:32
	ds_read_b128 v[100:103], v11 offset:48
	ds_read_b128 v[72:75], v10 offset:8448
	ds_read_b128 v[64:67], v10 offset:256
	ds_read_b128 v[68:71], v10 offset:4352
	ds_read_b128 v[76:79], v10 offset:12544
	ds_read_b128 v[84:87], v10 offset:16640
	s_waitcnt lgkmcnt(14)
	v_add_f32_dpp v122, v120, v120 quad_perm:[1,0,3,2] row_mask:0xf bank_mask:0xf bound_ctrl:1
	s_nop 1
	v_add_f32_dpp v122, v122, v122 quad_perm:[2,3,0,1] row_mask:0xf bank_mask:0xf bound_ctrl:1
	s_nop 1
	v_add_f32_dpp v122, v122, v122 row_half_mirror row_mask:0xf bank_mask:0xf bound_ctrl:1
	s_nop 1
	v_add_f32_dpp v122, v122, v122 row_mirror row_mask:0xf bank_mask:0xf bound_ctrl:1
	s_nop 0
	v_fmac_f32_e32 v120, 0xbd800000, v122
	v_mul_f32_e32 v122, 0x3d800000, v122
	v_cvt_pk_bf16_f32 v124, v120, v120
	global_store_dword v32, v122, s[14:15]
	global_store_short v31, v124, s[10:11]
	s_add_u32 s10, s10, 0x8000
	s_addc_u32 s11, s11, 0
	s_add_u32 s14, s14, 0x1000
	s_addc_u32 s15, s15, 0
	s_mov_b32 s1, s29
	s_add_i32 s0, s0, 1
	s_cmp_lg_u32 s0, 513
	s_cbranch_scc1 .Lrw_chunk
	s_waitcnt lgkmcnt(0)
	s_setprio 0
	s_branch .LBB0_504
